# mix_b: top-k compaction loop rewritten by hand, 8 consecutive keys per lane with ballot masks, same selected set
# speedup vs baseline: 1.3533x; 1.0098x over previous
; DI void phase_mix_b(int wv_, int vb_, int nvb_, char* ws_, const Ctx& p, char* smem) {
;     ...
;       } else {
;         int eqseen = 0;
;         const unsigned long long lt = (1ull << lane) - 1ull;
;         for (int j0 = 0; j0 < n; j0 += 64) {
;           const int j = j0 + lane; const bool v = j < n;
;           unsigned u = v ? (unsigned)myS[j] : 0u;
;           const bool gt = v && (u > prefix), eq = v && (u == prefix);
;           unsigned long long be = __ballot(eq);
;           const bool take = gt || (eq && (eqseen + __popcll(be & lt) < need));
;           unsigned long long bt = __ballot(take);
;           int pos = cnt + __popcll(bt & lt);
;           if (take && pos < 256) mySel[pos] = (u16)j;
;           cnt += __popcll(bt); eqseen += __popcll(be);
;         }
;         if (cnt > 256) cnt = 256;
;       }
.LBB0_429:
	v_lshl_add_u32 v4, v0, 1, v130
	v_cmp_lt_i32_e32 vcc, s22, v6
	v_lshlrev_b32_e32 v2, 1, v7
	s_and_saveexec_b64 s[2:3], vcc
	s_xor_b64 s[10:11], exec, s[2:3]
	s_cbranch_execz .LBB0_437
	v_lshlrev_b32_e32 v2, 1, v7
	s_mov_b64 s[96:97], exec
	v_lshlrev_b32_e32 v14, 4, v7
	v_add3_u32 v5, v12, v14, v214
	v_add3_u32 v14, v6, v7, 1
	v_xor_b32_e32 v15, v14, v6
	v_cmp_gt_u32_e32 vcc, 8, v15
	v_add_u32_e32 v15, v12, v214
	v_lshl_add_u32 v15, v14, 1, v15
	s_and_b64 exec, vcc, s[96:97]
	ds_write_b16 v15, v1
	s_mov_b64 exec, s[96:97]
	v_readfirstlane_b32 s62, v4
	v_readfirstlane_b32 s99, v10
	v_readfirstlane_b32 s98, v6
	v_lshlrev_b32_e32 v20, 3, v7
	s_lshl_b32 s99, s99, 1
	s_sub_i32 s99, s62, s99
	s_add_i32 s99, s99, 0x200
	s_lshr_b32 s98, s98, 9
	s_add_i32 s98, s98, 1
	ds_read_b128 v[16:19], v5
.Lmb_cloop:
	v_cmp_le_i32_e32 vcc, v20, v6
	s_waitcnt lgkmcnt(0)
	s_and_b64 exec, vcc, s[96:97]
	v_cmp_gt_u32_sdwa s[2:3], v16, v11 src0_sel:WORD_0 src1_sel:DWORD
	v_cmp_eq_u32_sdwa vcc, v16, v11 src0_sel:WORD_0 src1_sel:DWORD
	s_mov_b64 s[100:101], vcc
	v_cmp_gt_u32_sdwa s[4:5], v16, v11 src0_sel:WORD_1 src1_sel:DWORD
	v_cmp_eq_u32_sdwa vcc, v16, v11 src0_sel:WORD_1 src1_sel:DWORD
	s_or_b64 s[100:101], s[100:101], vcc
	v_cmp_gt_u32_sdwa s[6:7], v17, v11 src0_sel:WORD_0 src1_sel:DWORD
	v_cmp_eq_u32_sdwa vcc, v17, v11 src0_sel:WORD_0 src1_sel:DWORD
	s_or_b64 s[100:101], s[100:101], vcc
	v_cmp_gt_u32_sdwa s[8:9], v17, v11 src0_sel:WORD_1 src1_sel:DWORD
	v_cmp_eq_u32_sdwa vcc, v17, v11 src0_sel:WORD_1 src1_sel:DWORD
	s_or_b64 s[100:101], s[100:101], vcc
	v_cmp_gt_u32_sdwa s[12:13], v18, v11 src0_sel:WORD_0 src1_sel:DWORD
	v_cmp_eq_u32_sdwa vcc, v18, v11 src0_sel:WORD_0 src1_sel:DWORD
	s_or_b64 s[100:101], s[100:101], vcc
	v_cmp_gt_u32_sdwa s[14:15], v18, v11 src0_sel:WORD_1 src1_sel:DWORD
	v_cmp_eq_u32_sdwa vcc, v18, v11 src0_sel:WORD_1 src1_sel:DWORD
	s_or_b64 s[100:101], s[100:101], vcc
	v_cmp_gt_u32_sdwa s[18:19], v19, v11 src0_sel:WORD_0 src1_sel:DWORD
	v_cmp_eq_u32_sdwa vcc, v19, v11 src0_sel:WORD_0 src1_sel:DWORD
	s_or_b64 s[100:101], s[100:101], vcc
	v_cmp_gt_u32_sdwa s[34:35], v19, v11 src0_sel:WORD_1 src1_sel:DWORD
	v_cmp_eq_u32_sdwa vcc, v19, v11 src0_sel:WORD_1 src1_sel:DWORD
	s_or_b64 s[100:101], s[100:101], vcc
	s_mov_b64 exec, s[96:97]
	s_cmp_lg_u64 s[100:101], 0
	s_cbranch_scc1 .Lmb_cslow
	ds_read_b128 v[16:19], v5 offset:1024
	v_mbcnt_lo_u32_b32 v13, s2, 0
	v_mbcnt_hi_u32_b32 v13, s3, v13
	v_mbcnt_lo_u32_b32 v13, s4, v13
	v_mbcnt_hi_u32_b32 v13, s5, v13
	v_mbcnt_lo_u32_b32 v13, s6, v13
	v_mbcnt_hi_u32_b32 v13, s7, v13
	v_mbcnt_lo_u32_b32 v13, s8, v13
	v_mbcnt_hi_u32_b32 v13, s9, v13
	v_mbcnt_lo_u32_b32 v13, s12, v13
	v_mbcnt_hi_u32_b32 v13, s13, v13
	v_mbcnt_lo_u32_b32 v13, s14, v13
	v_mbcnt_hi_u32_b32 v13, s15, v13
	v_mbcnt_lo_u32_b32 v13, s18, v13
	v_mbcnt_hi_u32_b32 v13, s19, v13
	v_mbcnt_lo_u32_b32 v13, s34, v13
	v_mbcnt_hi_u32_b32 v13, s35, v13
	v_lshl_add_u32 v13, v13, 1, s62
	s_mov_b64 exec, s[2:3]
	ds_write_b16 v13, v20
	v_add_u32_e32 v13, 2, v13
	s_mov_b64 exec, s[4:5]
	v_add_u32_e32 v15, 1, v20
	ds_write_b16 v13, v15
	v_add_u32_e32 v13, 2, v13
	s_mov_b64 exec, s[6:7]
	v_add_u32_e32 v15, 2, v20
	ds_write_b16 v13, v15
	v_add_u32_e32 v13, 2, v13
	s_mov_b64 exec, s[8:9]
	v_add_u32_e32 v15, 3, v20
	ds_write_b16 v13, v15
	v_add_u32_e32 v13, 2, v13
	s_mov_b64 exec, s[12:13]
	v_add_u32_e32 v15, 4, v20
	ds_write_b16 v13, v15
	v_add_u32_e32 v13, 2, v13
	s_mov_b64 exec, s[14:15]
	v_add_u32_e32 v15, 5, v20
	ds_write_b16 v13, v15
	v_add_u32_e32 v13, 2, v13
	s_mov_b64 exec, s[18:19]
	v_add_u32_e32 v15, 6, v20
	ds_write_b16 v13, v15
	v_add_u32_e32 v13, 2, v13
	s_mov_b64 exec, s[34:35]
	v_add_u32_e32 v15, 7, v20
	ds_write_b16 v13, v15
	v_add_u32_e32 v13, 2, v13
	s_mov_b64 exec, s[96:97]
	v_readlane_b32 s62, v13, 63
.Lmb_ctail:
	v_add_u32_e32 v5, 0x400, v5
	v_add_u32_e32 v20, 0x200, v20
	s_sub_i32 s98, s98, 1
	s_cmp_lg_u32 s98, 0
	s_cbranch_scc1 .Lmb_cloop
	s_waitcnt lgkmcnt(0)
	v_sub_u32_e32 v12, s62, v4
	v_lshrrev_b32_e32 v12, 1, v12
	v_add_u32_e32 v12, v12, v10
	s_branch .Lmb_cdone
; DI void phase_mix_b(int wv_, int vb_, int nvb_, char* ws_, const Ctx& p, char* smem) {
;     ...
;       } else {
;         int eqseen = 0;
;         const unsigned long long lt = (1ull << lane) - 1ull;
;         for (int j0 = 0; j0 < n; j0 += 64) {
;           const int j = j0 + lane; const bool v = j < n;
;           unsigned u = v ? (unsigned)myS[j] : 0u;
;           const bool gt = v && (u > prefix), eq = v && (u == prefix);
;           unsigned long long be = __ballot(eq);
;           const bool take = gt || (eq && (eqseen + __popcll(be & lt) < need));
;           unsigned long long bt = __ballot(take);
;           int pos = cnt + __popcll(bt & lt);
;           if (take && pos < 256) mySel[pos] = (u16)j;
;           cnt += __popcll(bt); eqseen += __popcll(be);
;         }
;         if (cnt > 256) cnt = 256;
;       }
.Lmb_cslow:
	v_mbcnt_lo_u32_b32 v13, s2, 0
	v_mbcnt_hi_u32_b32 v13, s3, v13
	v_mbcnt_lo_u32_b32 v13, s4, v13
	v_mbcnt_hi_u32_b32 v13, s5, v13
	v_mbcnt_lo_u32_b32 v13, s6, v13
	v_mbcnt_hi_u32_b32 v13, s7, v13
	v_mbcnt_lo_u32_b32 v13, s8, v13
	v_mbcnt_hi_u32_b32 v13, s9, v13
	v_mbcnt_lo_u32_b32 v13, s12, v13
	v_mbcnt_hi_u32_b32 v13, s13, v13
	v_mbcnt_lo_u32_b32 v13, s14, v13
	v_mbcnt_hi_u32_b32 v13, s15, v13
	v_mbcnt_lo_u32_b32 v13, s18, v13
	v_mbcnt_hi_u32_b32 v13, s19, v13
	v_mbcnt_lo_u32_b32 v13, s34, v13
	v_mbcnt_hi_u32_b32 v13, s35, v13
	v_lshl_add_u32 v13, v13, 1, s62
	s_mov_b64 exec, s[2:3]
	ds_write_b16 v13, v20
	v_add_u32_e32 v13, 2, v13
	s_mov_b64 exec, s[4:5]
	v_add_u32_e32 v15, 1, v20
	ds_write_b16 v13, v15
	v_add_u32_e32 v13, 2, v13
	s_mov_b64 exec, s[6:7]
	v_add_u32_e32 v15, 2, v20
	ds_write_b16 v13, v15
	v_add_u32_e32 v13, 2, v13
	s_mov_b64 exec, s[8:9]
	v_add_u32_e32 v15, 3, v20
	ds_write_b16 v13, v15
	v_add_u32_e32 v13, 2, v13
	s_mov_b64 exec, s[12:13]
	v_add_u32_e32 v15, 4, v20
	ds_write_b16 v13, v15
	v_add_u32_e32 v13, 2, v13
	s_mov_b64 exec, s[14:15]
	v_add_u32_e32 v15, 5, v20
	ds_write_b16 v13, v15
	v_add_u32_e32 v13, 2, v13
	s_mov_b64 exec, s[18:19]
	v_add_u32_e32 v15, 6, v20
	ds_write_b16 v13, v15
	v_add_u32_e32 v13, 2, v13
	s_mov_b64 exec, s[34:35]
	v_add_u32_e32 v15, 7, v20
	ds_write_b16 v13, v15
	v_add_u32_e32 v13, 2, v13
	s_mov_b64 exec, s[96:97]
	v_readlane_b32 s62, v13, 63
	v_cmp_le_i32_e32 vcc, v20, v6
	s_nop 1
	s_and_b64 exec, vcc, s[96:97]
	v_cmp_eq_u32_sdwa s[2:3], v16, v11 src0_sel:WORD_0 src1_sel:DWORD
	v_cmp_eq_u32_sdwa s[4:5], v16, v11 src0_sel:WORD_1 src1_sel:DWORD
	v_cmp_eq_u32_sdwa s[6:7], v17, v11 src0_sel:WORD_0 src1_sel:DWORD
	v_cmp_eq_u32_sdwa s[8:9], v17, v11 src0_sel:WORD_1 src1_sel:DWORD
	v_cmp_eq_u32_sdwa s[12:13], v18, v11 src0_sel:WORD_0 src1_sel:DWORD
	v_cmp_eq_u32_sdwa s[14:15], v18, v11 src0_sel:WORD_1 src1_sel:DWORD
	v_cmp_eq_u32_sdwa s[18:19], v19, v11 src0_sel:WORD_0 src1_sel:DWORD
	v_cmp_eq_u32_sdwa s[34:35], v19, v11 src0_sel:WORD_1 src1_sel:DWORD
	s_mov_b64 exec, s[96:97]
	ds_read_b128 v[16:19], v5 offset:1024
	v_mbcnt_lo_u32_b32 v13, s2, 0
	v_mbcnt_hi_u32_b32 v13, s3, v13
	v_mbcnt_lo_u32_b32 v13, s4, v13
	v_mbcnt_hi_u32_b32 v13, s5, v13
	v_mbcnt_lo_u32_b32 v13, s6, v13
	v_mbcnt_hi_u32_b32 v13, s7, v13
	v_mbcnt_lo_u32_b32 v13, s8, v13
	v_mbcnt_hi_u32_b32 v13, s9, v13
	v_mbcnt_lo_u32_b32 v13, s12, v13
	v_mbcnt_hi_u32_b32 v13, s13, v13
	v_mbcnt_lo_u32_b32 v13, s14, v13
	v_mbcnt_hi_u32_b32 v13, s15, v13
	v_mbcnt_lo_u32_b32 v13, s18, v13
	v_mbcnt_hi_u32_b32 v13, s19, v13
	v_mbcnt_lo_u32_b32 v13, s34, v13
	v_mbcnt_hi_u32_b32 v13, s35, v13
	v_lshl_add_u32 v13, v13, 1, s99
	v_add_u32_e32 v14, 0x200, v4
	s_mov_b64 exec, s[2:3]
	v_cmp_lt_u32_e32 vcc, v13, v14
	v_add_u32_e32 v15, 0, v20
	s_and_b64 exec, exec, vcc
	ds_write_b16 v13, v15
	s_mov_b64 exec, s[2:3]
	v_add_u32_e32 v13, 2, v13
	s_mov_b64 exec, s[4:5]
	v_cmp_lt_u32_e32 vcc, v13, v14
	v_add_u32_e32 v15, 1, v20
	s_and_b64 exec, exec, vcc
	ds_write_b16 v13, v15
	s_mov_b64 exec, s[4:5]
	v_add_u32_e32 v13, 2, v13
	s_mov_b64 exec, s[6:7]
	v_cmp_lt_u32_e32 vcc, v13, v14
	v_add_u32_e32 v15, 2, v20
	s_and_b64 exec, exec, vcc
	ds_write_b16 v13, v15
	s_mov_b64 exec, s[6:7]
	v_add_u32_e32 v13, 2, v13
	s_mov_b64 exec, s[8:9]
	v_cmp_lt_u32_e32 vcc, v13, v14
	v_add_u32_e32 v15, 3, v20
	s_and_b64 exec, exec, vcc
	ds_write_b16 v13, v15
	s_mov_b64 exec, s[8:9]
	v_add_u32_e32 v13, 2, v13
	s_mov_b64 exec, s[12:13]
	v_cmp_lt_u32_e32 vcc, v13, v14
	v_add_u32_e32 v15, 4, v20
	s_and_b64 exec, exec, vcc
	ds_write_b16 v13, v15
	s_mov_b64 exec, s[12:13]
	v_add_u32_e32 v13, 2, v13
	s_mov_b64 exec, s[14:15]
	v_cmp_lt_u32_e32 vcc, v13, v14
	v_add_u32_e32 v15, 5, v20
	s_and_b64 exec, exec, vcc
	ds_write_b16 v13, v15
	s_mov_b64 exec, s[14:15]
	v_add_u32_e32 v13, 2, v13
	s_mov_b64 exec, s[18:19]
	v_cmp_lt_u32_e32 vcc, v13, v14
	v_add_u32_e32 v15, 6, v20
	s_and_b64 exec, exec, vcc
	ds_write_b16 v13, v15
	s_mov_b64 exec, s[18:19]
	v_add_u32_e32 v13, 2, v13
	s_mov_b64 exec, s[34:35]
	v_cmp_lt_u32_e32 vcc, v13, v14
	v_add_u32_e32 v15, 7, v20
	s_and_b64 exec, exec, vcc
	ds_write_b16 v13, v15
	s_mov_b64 exec, s[34:35]
	v_add_u32_e32 v13, 2, v13
	s_mov_b64 exec, s[96:97]
	s_nop 0
	v_readlane_b32 s99, v13, 63
	s_branch .Lmb_ctail
.Lmb_cdone:
	v_min_i32_e32 v0, 0x100, v12
